# attention K/Q-norm staging: xor-1/2/4 lane exchanges as DPP moves instead of ds_bpermute
# speedup vs baseline: 1.0054x; 1.0054x over previous
; #define LAS __attribute__((address_space(3)))
; __device__ __forceinline__ float bflo(unsigned u) { return __uint_as_float(u << 16); }
; __device__ __forceinline__ float bfhi(unsigned u) { return __uint_as_float(u & 0xffff0000u); }
; __device__ __forceinline__ unsigned pk2(float lo, float hi) { f32x2_t v = {lo, hi}; bf16x2_t b = __builtin_convertvector(v, bf16x2_t); return __builtin_bit_cast(unsigned, b); }
; __device__ __forceinline__ void attn_phase(LAS unsigned char* lds, const bf16* PROJ, const bf16* Ygate, bf16* OG0, bf16* OG1, bf16* OG2, float* LSE, const float* qnw, const float* knw, int bx, int G) {
;     ...
;         const int sub = t & 15, gi = (t >> 4) % 3, bh = t / 48, h = bh & 15, bl = bh >> 4;
;         const int sh = 2 * gi, d = 1 << sh, r = sub & (d - 1), n = sub >> sh;
;         const float ad = exp2f(-8.f * (float)(gi * 16 + h + 1) / 48.f) * (float)d;
;         bf16* OG = gi == 0 ? OG0 : (gi == 1 ? OG1 : OG2);
;         {
;             const f32x4 kw0 = *(const f32x4*)(knw + gi * 64 + 8 * oct), kw1 = *(const f32x4*)(knw + gi * 64 + 8 * oct + 4);
; #pragma unroll
;             for (int jj = 0; jj < 4; ++jj) {
;                 const int key = (tid >> 3) + 64 * jj; const v4u kq = kr[half][jj];
;                 float kf[8] = {bflo(kq.x), bfhi(kq.x), bflo(kq.y), bfhi(kq.y), bflo(kq.z), bfhi(kq.z), bflo(kq.w), bfhi(kq.w)};
;                 float ss = 0.f;
; #pragma unroll
;                 for (int e = 0; e < 8; ++e) ss += kf[e] * kf[e];
;                 ss += __shfl_xor(ss, 1); ss += __shfl_xor(ss, 2); ss += __shfl_xor(ss, 4);
;                 const float rs = rsqrtf(ss * (1.f / 64.f) + EPS);
;                 v4u ko; ko.x = pk2(kf[0] * rs * kw0[0], kf[1] * rs * kw0[1]); ko.y = pk2(kf[2] * rs * kw0[2], kf[3] * rs * kw0[3]);
;                 ko.z = pk2(kf[4] * rs * kw1[0], kf[5] * rs * kw1[1]); ko.w = pk2(kf[6] * rs * kw1[2], kf[7] * rs * kw1[3]);
;                 *(LAS v4u*)(Ks + key * 72 + 8 * oct) = ko;
;                 *(LAS v4u*)(Vs + key * 80 + 8 * oct) = vr[half][jj];
;             }
.LBB0_269:
	s_ashr_i32 s0, s51, 4
	s_mul_hi_i32 s1, s0, 0x55555556
	s_lshr_b32 s2, s1, 31
	s_add_i32 s1, s1, s2
	s_mul_i32 s1, s1, 3
	s_sub_i32 s2, s0, s1
	s_mul_hi_i32 s0, s51, 0x2aaaaaab
	s_lshl_b32 s3, s2, 1
	s_and_b32 s20, s51, 15
	s_lshr_b32 s1, s0, 31
	s_ashr_i32 s21, s0, 3
	s_bfm_b32 s0, s3, 0
	s_and_b32 s22, s0, s20
	s_lshl_b32 s0, s2, 6
	s_add_i32 s21, s21, s1
	s_ashr_i32 s1, s0, 31
	s_lshl_b64 s[24:25], s[0:1], 2
	v_lshl_add_u64 v[2:3], v[110:111], 0, s[24:25]
	global_load_dwordx4 v[84:87], v[2:3], off offset:16
	global_load_dwordx4 v[88:91], v[2:3], off
	s_waitcnt vmcnt(5)
	v_lshlrev_b32_e32 v102, 16, v8
	v_and_b32_e32 v103, 0xffff0000, v8
	v_lshlrev_b32_e32 v98, 16, v9
	v_and_b32_e32 v99, 0xffff0000, v9
	v_pk_mul_f32 v[104:105], v[102:103], v[102:103]
	v_pk_mul_f32 v[100:101], v[98:99], v[98:99]
	v_add_f32_e32 v1, v104, v105
	v_lshlrev_b32_e32 v94, 16, v10
	v_and_b32_e32 v95, 0xffff0000, v10
	v_add_f32_e32 v1, v100, v1
	v_pk_mul_f32 v[96:97], v[94:95], v[94:95]
	v_add_f32_e32 v1, v101, v1
	v_lshlrev_b32_e32 v2, 16, v11
	v_and_b32_e32 v3, 0xffff0000, v11
	v_add_f32_e32 v1, v96, v1
	v_pk_mul_f32 v[92:93], v[2:3], v[2:3]
	v_add_f32_e32 v1, v97, v1
	v_add_f32_e32 v1, v92, v1
	v_add_f32_e32 v1, v93, v1
	s_nop 1
	v_mov_b32_dpp v92, v1 quad_perm:[1,0,3,2] row_mask:0xf bank_mask:0xf
	v_lshlrev_b32_e32 v156, 16, v20
	v_and_b32_e32 v157, 0xffff0000, v20
	v_lshlrev_b32_e32 v152, 16, v21
	v_and_b32_e32 v153, 0xffff0000, v21
	s_waitcnt lgkmcnt(0)
	v_add_f32_e32 v1, v1, v92
	s_nop 1
	v_mov_b32_dpp v92, v1 quad_perm:[2,3,0,1] row_mask:0xf bank_mask:0xf
	v_pk_mul_f32 v[158:159], v[156:157], v[156:157]
	v_pk_mul_f32 v[154:155], v[152:153], v[152:153]
	v_mov_b32_e32 v162, v158
	v_lshlrev_b32_e32 v136, 16, v22
	s_waitcnt lgkmcnt(0)
	v_add_f32_e32 v1, v1, v92
	s_nop 1
	v_mov_b32_dpp v92, v1 row_half_mirror row_mask:0xf bank_mask:0xf
	v_and_b32_e32 v137, 0xffff0000, v22
	v_mov_b32_e32 v158, v154
	v_pk_mul_f32 v[150:151], v[136:137], v[136:137]
	v_lshlrev_b32_e32 v106, 16, v23
	s_waitcnt lgkmcnt(0)
	v_add_f32_e32 v1, v1, v92
	v_fmamk_f32 v1, v1, 0x3c800000, v139
	v_cmp_gt_f32_e32 vcc, s33, v1
	v_mul_f32_e32 v92, 0x4b800000, v1
	v_and_b32_e32 v107, 0xffff0000, v23
	v_cndmask_b32_e32 v1, v1, v92, vcc
	v_rsq_f32_e32 v1, v1
	v_pk_mul_f32 v[134:135], v[106:107], v[106:107]
	s_mov_b32 s0, 0x358637bd
	s_mov_b32 s26, 0x3c800000
	v_mul_f32_e32 v92, 0x45800000, v1
	v_cndmask_b32_e32 v96, v1, v92, vcc
	v_pk_mul_f32 v[92:93], v[96:97], v[102:103] op_sel_hi:[0,1]
	v_pk_mul_f32 v[98:99], v[96:97], v[98:99] op_sel_hi:[0,1]
	v_pk_mul_f32 v[94:95], v[96:97], v[94:95] op_sel_hi:[0,1]
	v_pk_mul_f32 v[2:3], v[96:97], v[2:3] op_sel_hi:[0,1]
	v_lshlrev_b32_e32 v102, 16, v4
	v_and_b32_e32 v103, 0xffff0000, v4
	v_pk_mul_f32 v[104:105], v[102:103], v[102:103]
	s_waitcnt vmcnt(3)
	v_and_b32_e32 v179, 0xffff0000, v48
	v_mov_b32_e32 v163, v104
	v_mov_b32_e32 v104, v159
	v_pk_add_f32 v[104:105], v[162:163], v[104:105]
	v_lshlrev_b32_e32 v178, 16, v48
	v_mul_f32_e32 v240, v179, v179
	v_lshlrev_b32_e32 v176, 16, v49
	v_and_b32_e32 v177, 0xffff0000, v49
	v_pk_fma_f32 v[240:241], v[178:179], v[178:179], v[240:241] op_sel_hi:[1,1,0]
	v_mul_f32_e32 v242, v177, v177
	v_pk_fma_f32 v[240:241], v[176:177], v[176:177], v[240:241]
	v_lshlrev_b32_e32 v174, 16, v50
	v_and_b32_e32 v175, 0xffff0000, v50
	v_pk_add_f32 v[240:241], v[242:243], v[240:241] op_sel_hi:[0,1]
	v_pk_fma_f32 v[240:241], v[174:175], v[174:175], v[240:241]
	v_mul_f32_e32 v242, v175, v175
	v_lshlrev_b32_e32 v172, 16, v51
	v_and_b32_e32 v173, 0xffff0000, v51
	v_pk_add_f32 v[240:241], v[242:243], v[240:241] op_sel_hi:[0,1]
	v_add_u32_e32 v231, v113, v188
	v_lshlrev_b32_e32 v162, 16, v40
	v_and_b32_e32 v163, 0xffff0000, v40
	s_waitcnt vmcnt(2)
	v_lshlrev_b32_e32 v170, 16, v52
	s_waitcnt vmcnt(1)
	v_pk_mul_f32 v[94:95], v[84:85], v[94:95]
	s_waitcnt vmcnt(0)
	v_pk_mul_f32 v[92:93], v[88:89], v[92:93]
	v_pk_mul_f32 v[98:99], v[90:91], v[98:99]
	v_cvt_pk_bf16_f32 v92, v92, v93
	v_cvt_pk_bf16_f32 v93, v98, v99
	v_pk_mul_f32 v[2:3], v[86:87], v[2:3]
	v_lshlrev_b32_e32 v98, 16, v5
	v_and_b32_e32 v99, 0xffff0000, v5
	v_cvt_pk_bf16_f32 v94, v94, v95
	v_cvt_pk_bf16_f32 v95, v2, v3
	v_pk_mul_f32 v[100:101], v[98:99], v[98:99]
	ds_write_b128 v229, v[92:95]
	v_lshlrev_b32_e32 v94, 16, v6
	v_and_b32_e32 v95, 0xffff0000, v6
	v_mov_b32_e32 v159, v100
	v_pk_mul_f32 v[96:97], v[94:95], v[94:95]
	v_pk_add_f32 v[104:105], v[158:159], v[104:105]
	v_mov_b32_e32 v100, v155
	v_lshlrev_b32_e32 v2, 16, v7
	v_and_b32_e32 v3, 0xffff0000, v7
	v_pk_add_f32 v[100:101], v[100:101], v[104:105]
	v_mov_b32_e32 v104, v150
	v_mov_b32_e32 v105, v96
	v_pk_mul_f32 v[92:93], v[2:3], v[2:3]
	v_pk_add_f32 v[100:101], v[104:105], v[100:101]
	v_mov_b32_e32 v96, v151
	v_pk_add_f32 v[96:97], v[96:97], v[100:101]
	v_mov_b32_e32 v100, v134
	v_mov_b32_e32 v101, v92
	v_pk_add_f32 v[96:97], v[100:101], v[96:97]
	v_mov_b32_e32 v92, v135
	v_pk_add_f32 v[92:93], v[92:93], v[96:97]
	s_nop 1
	v_mov_b32_dpp v97, v93 quad_perm:[1,0,3,2] row_mask:0xf bank_mask:0xf
	s_nop 1
	v_mov_b32_dpp v96, v92 quad_perm:[1,0,3,2] row_mask:0xf bank_mask:0xf
	v_mov_b64_e32 v[134:135], s[0:1]
	v_and_b32_e32 v171, 0xffff0000, v52
	v_pk_fma_f32 v[240:241], v[172:173], v[172:173], v[240:241]
	v_mul_f32_e32 v242, v173, v173
	s_waitcnt lgkmcnt(0)
	v_pk_add_f32 v[92:93], v[92:93], v[96:97]
	s_nop 1
	v_mov_b32_dpp v97, v93 quad_perm:[2,3,0,1] row_mask:0xf bank_mask:0xf
	s_nop 1
	v_mov_b32_dpp v96, v92 quad_perm:[2,3,0,1] row_mask:0xf bank_mask:0xf
	ds_write_b128 v231, v[12:15] offset:36864
	v_pk_mul_f32 v[180:181], v[162:163], v[162:163]
	v_pk_mul_f32 v[238:239], v[170:171], v[170:171]
	v_pk_add_f32 v[240:241], v[242:243], v[240:241] op_sel_hi:[0,1]
	s_waitcnt lgkmcnt(1)
; #define LAS __attribute__((address_space(3)))
; __device__ __forceinline__ void attn_phase(LAS unsigned char* lds, const bf16* PROJ, const bf16* Ygate, bf16* OG0, bf16* OG1, bf16* OG2, float* LSE, const float* qnw, const float* knw, int bx, int G) {
;     ...
;             const f32x4 kw0 = *(const f32x4*)(knw + gi * 64 + 8 * oct), kw1 = *(const f32x4*)(knw + gi * 64 + 8 * oct + 4);
; #pragma unroll
;             for (int jj = 0; jj < 4; ++jj) {
;                 const int key = (tid >> 3) + 64 * jj; const v4u kq = kr[half][jj];
;                 float kf[8] = {bflo(kq.x), bfhi(kq.x), bflo(kq.y), bfhi(kq.y), bflo(kq.z), bfhi(kq.z), bflo(kq.w), bfhi(kq.w)};
;                 float ss = 0.f;
; #pragma unroll
;                 for (int e = 0; e < 8; ++e) ss += kf[e] * kf[e];
;                 ss += __shfl_xor(ss, 1); ss += __shfl_xor(ss, 2); ss += __shfl_xor(ss, 4);
;                 const float rs = rsqrtf(ss * (1.f / 64.f) + EPS);
;                 v4u ko; ko.x = pk2(kf[0] * rs * kw0[0], kf[1] * rs * kw0[1]); ko.y = pk2(kf[2] * rs * kw0[2], kf[3] * rs * kw0[3]);
;                 ko.z = pk2(kf[4] * rs * kw1[0], kf[5] * rs * kw1[1]); ko.w = pk2(kf[6] * rs * kw1[2], kf[7] * rs * kw1[3]);
;                 *(LAS v4u*)(Ks + key * 72 + 8 * oct) = ko;
;                 *(LAS v4u*)(Vs + key * 80 + 8 * oct) = vr[half][jj];
;             }
;         }
;         const int qi = 16 * w + l16;
;         const size_t qrow = (size_t)bl * SEQL + (size_t)(128 * n + qi) * d + r;
;         bf16x8 qreg[2];
;         {
;             float qf[2][8]; float ss = 0.f;
; #pragma unroll
;             for (int ks = 0; ks < 2; ++ks) {
;                 const v4u qq = qr[half][ks];
;                 qf[ks][0] = bflo(qq.x); qf[ks][1] = bfhi(qq.x); qf[ks][2] = bflo(qq.y); qf[ks][3] = bfhi(qq.y); qf[ks][4] = bflo(qq.z); qf[ks][5] = bfhi(qq.z); qf[ks][6] = bflo(qq.w); qf[ks][7] = bfhi(qq.w);
; #pragma unroll
;                 for (int e = 0; e < 8; ++e) ss += qf[ks][e] * qf[ks][e];
;             }
;             ss += __shfl_xor(ss, 16); ss += __shfl_xor(ss, 32);
;             const float rs = rsqrtf(ss * (1.f / 64.f) + EPS) * 0.125f;
; #pragma unroll
;             for (int ks = 0; ks < 2; ++ks) {
;                 const f32x4 w0 = *(const f32x4*)(qnw + gi * 64 + 32 * ks + 8 * g4), w1 = *(const f32x4*)(qnw + gi * 64 + 32 * ks + 8 * g4 + 4);
	v_pk_add_f32 v[92:93], v[92:93], v[96:97]
	s_nop 1
	v_mov_b32_dpp v97, v93 row_half_mirror row_mask:0xf bank_mask:0xf
	s_nop 1
	v_mov_b32_dpp v96, v92 row_half_mirror row_mask:0xf bank_mask:0xf
	v_lshlrev_b32_e32 v168, 16, v53
	v_and_b32_e32 v169, 0xffff0000, v53
	v_mov_b32_e32 v242, v238
	v_mov_b32_e32 v243, v180
	s_waitcnt lgkmcnt(0)
	v_pk_add_f32 v[92:93], v[92:93], v[96:97]
	v_mov_b32_e32 v241, v181
	v_pk_fma_f32 v[96:97], v[92:93], s[26:27], v[134:135] op_sel_hi:[1,0,0]
	v_pk_mul_f32 v[236:237], v[168:169], v[168:169]
	v_mul_f32_e32 v1, 0x4b800000, v97
	v_cmp_gt_f32_e64 s[0:1], s33, v97
	v_cmp_gt_f32_e32 vcc, s33, v96
	v_pk_add_f32 v[180:181], v[242:243], v[240:241]
	v_cndmask_b32_e64 v1, v97, v1, s[0:1]
	v_rsq_f32_e32 v1, v1
	v_lshlrev_b32_e32 v166, 16, v54
	v_and_b32_e32 v167, 0xffff0000, v54
	v_pk_mul_f32 v[234:235], v[166:167], v[166:167]
	v_mul_f32_e32 v92, 0x45800000, v1
	v_cndmask_b32_e64 v100, v1, v92, s[0:1]
	v_mul_f32_e32 v1, 0x4b800000, v96
	v_cndmask_b32_e32 v1, v96, v1, vcc
	v_rsq_f32_e32 v1, v1
	v_pk_mul_f32 v[94:95], v[100:101], v[94:95] op_sel_hi:[0,1]
	v_pk_mul_f32 v[2:3], v[100:101], v[2:3] op_sel_hi:[0,1]
	v_pk_mul_f32 v[92:93], v[100:101], v[102:103] op_sel_hi:[0,1]
	v_pk_mul_f32 v[98:99], v[100:101], v[98:99] op_sel_hi:[0,1]
	v_pk_mul_f32 v[94:95], v[84:85], v[94:95]
	v_pk_mul_f32 v[2:3], v[86:87], v[2:3]
	v_pk_mul_f32 v[92:93], v[88:89], v[92:93]
	v_pk_mul_f32 v[98:99], v[90:91], v[98:99]
	v_cvt_pk_bf16_f32 v94, v94, v95
	v_cvt_pk_bf16_f32 v95, v2, v3
	v_mul_f32_e32 v2, 0x45800000, v1
	v_cvt_pk_bf16_f32 v92, v92, v93
	v_cvt_pk_bf16_f32 v93, v98, v99
	v_cndmask_b32_e32 v2, v1, v2, vcc
	ds_write_b128 v229, v[92:95] offset:9216
	ds_write_b128 v231, v[16:19] offset:47104
	v_pk_mul_f32 v[92:93], v[2:3], v[156:157] op_sel_hi:[0,1]
	v_lshlrev_b32_e32 v156, 16, v41
	v_and_b32_e32 v157, 0xffff0000, v41
	v_pk_mul_f32 v[158:159], v[156:157], v[156:157]
	v_pk_mul_f32 v[94:95], v[2:3], v[152:153] op_sel_hi:[0,1]
	v_lshlrev_b32_e32 v152, 16, v42
	v_and_b32_e32 v153, 0xffff0000, v42
	v_pk_mov_b32 v[238:239], v[238:239], v[158:159] op_sel:[1,0]
	v_pk_mul_f32 v[92:93], v[88:89], v[92:93]
	v_pk_mul_f32 v[94:95], v[90:91], v[94:95]
	v_pk_mul_f32 v[154:155], v[152:153], v[152:153]
	v_pk_add_f32 v[180:181], v[238:239], v[180:181]
	v_mov_b32_e32 v158, v236
	v_cvt_pk_bf16_f32 v92, v92, v93
	v_cvt_pk_bf16_f32 v93, v94, v95
	v_pk_mul_f32 v[94:95], v[2:3], v[136:137] op_sel_hi:[0,1]
	v_lshlrev_b32_e32 v136, 16, v43
	v_and_b32_e32 v137, 0xffff0000, v43
	v_pk_add_f32 v[158:159], v[158:159], v[180:181]
	v_pk_mov_b32 v[180:181], v[236:237], v[154:155] op_sel:[1,0]
	v_pk_mul_f32 v[150:151], v[136:137], v[136:137]
	v_lshlrev_b32_e32 v164, 16, v55
	v_and_b32_e32 v165, 0xffff0000, v55
	v_pk_add_f32 v[158:159], v[180:181], v[158:159]
	v_mov_b32_e32 v154, v234
	v_pk_mul_f32 v[232:233], v[164:165], v[164:165]
	v_pk_add_f32 v[154:155], v[154:155], v[158:159]
	v_pk_mov_b32 v[158:159], v[234:235], v[150:151] op_sel:[1,0]
	v_mov_b32_e32 v150, v232
	v_pk_add_f32 v[154:155], v[158:159], v[154:155]
	v_pk_mul_f32 v[2:3], v[2:3], v[106:107] op_sel_hi:[0,1]
	v_pk_add_f32 v[150:151], v[150:151], v[154:155]
	s_nop 1
	v_mov_b32_dpp v155, v151 quad_perm:[1,0,3,2] row_mask:0xf bank_mask:0xf
	v_mov_b32_e32 v154, v233
	v_pk_mul_f32 v[94:95], v[84:85], v[94:95]
	v_pk_mul_f32 v[2:3], v[86:87], v[2:3]
	s_ashr_i32 s0, s21, 4
	s_waitcnt lgkmcnt(0)
	v_pk_add_f32 v[150:151], v[154:155], v[150:151]
	s_nop 1
	v_mov_b32_dpp v155, v151 quad_perm:[2,3,0,1] row_mask:0xf bank_mask:0xf
	ds_bpermute_b32 v154, v189, v150
	s_lshr_b32 s54, s20, s3
	v_cvt_pk_bf16_f32 v94, v94, v95
	v_cvt_pk_bf16_f32 v95, v2, v3
	s_ashr_i32 s1, s0, 31
	s_waitcnt lgkmcnt(0)
	v_pk_add_f32 v[150:151], v[150:151], v[154:155]
	s_nop 1
	v_mov_b32_dpp v155, v151 row_half_mirror row_mask:0xf bank_mask:0xf
	ds_bpermute_b32 v154, v196, v150
	v_lshl_add_u32 v2, s54, 7, v147
	s_and_b32 s53, s21, 15
	s_lshl_b64 s[20:21], s[0:1], 11
	v_ashrrev_i32_e32 v3, 31, v2
	s_waitcnt lgkmcnt(0)
	v_pk_add_f32 v[150:151], v[150:151], v[154:155]
	s_or_b32 s20, s20, s22
	v_pk_fma_f32 v[180:181], v[150:151], s[26:27], v[134:135] op_sel_hi:[1,0,0]
	v_lshlrev_b64 v[2:3], s3, v[2:3]
	v_mul_f32_e32 v1, 0x4b800000, v181
	v_cmp_gt_f32_e32 vcc, s33, v181
	ds_write_b128 v229, v[92:95] offset:18432
	ds_write_b128 v231, v[24:27] offset:57344
	v_cndmask_b32_e32 v1, v181, v1, vcc
	v_rsq_f32_e32 v1, v1
	v_lshl_add_u64 v[96:97], v[114:115], 0, s[24:25]
	s_lshl_b32 s26, s53, 7
	global_load_dwordx4 v[100:103], v[96:97], off offset:16
	global_load_dwordx4 v[104:107], v[96:97], off
	global_load_dwordx4 v[92:95], v[96:97], off offset:144
	s_nop 0
	global_load_dwordx4 v[96:99], v[96:97], off offset:128
	v_mul_f32_e32 v134, 0x45800000, v1
	v_cndmask_b32_e32 v134, v1, v134, vcc
	v_pk_mul_f32 v[150:151], v[134:135], v[162:163] op_sel_hi:[0,1]
	v_pk_mul_f32 v[88:89], v[88:89], v[150:151]
	v_pk_mul_f32 v[150:151], v[134:135], v[156:157] op_sel_hi:[0,1]
	v_pk_mul_f32 v[90:91], v[90:91], v[150:151]
	v_cvt_pk_bf16_f32 v88, v88, v89
	v_cvt_pk_bf16_f32 v89, v90, v91
	v_pk_mul_f32 v[90:91], v[134:135], v[152:153] op_sel_hi:[0,1]
	v_pk_mul_f32 v[84:85], v[84:85], v[90:91]
	v_cmp_gt_f32_e64 s[0:1], s33, v180
	v_cvt_pk_bf16_f32 v90, v84, v85
	v_pk_mul_f32 v[84:85], v[134:135], v[136:137] op_sel_hi:[0,1]
	v_lshl_add_u64 v[136:137], s[20:21], 0, v[2:3]
	v_lshlrev_b64 v[162:163], 11, v[136:137]
	v_pk_mul_f32 v[84:85], v[86:87], v[84:85]
	v_lshl_add_u64 v[2:3], s[28:29], 0, v[162:163]
	v_cvt_pk_bf16_f32 v91, v84, v85
	v_lshl_add_u64 v[2:3], v[2:3], 0, s[26:27]
	v_lshlrev_b32_e32 v134, 1, v112
	v_mov_b32_e32 v135, v0
	ds_write_b128 v229, v[88:91] offset:27648
	ds_write_b128 v230, v[44:47] offset:57344
	v_lshl_add_u64 v[2:3], v[2:3], 0, v[134:135]
	global_load_dwordx4 v[88:91], v[2:3], off
	global_load_dwordx4 v[84:87], v[2:3], off offset:64
	v_readlane_b32 s20, v252, 59
	s_add_i32 s52, s51, s20
	s_waitcnt lgkmcnt(0)
	s_barrier
; __device__ __forceinline__ void attn_phase(LAS unsigned char* lds, const bf16* PROJ, const bf16* Ygate, bf16* OG0, bf16* OG1, bf16* OG2, float* LSE, const float* qnw, const float* knw, int bx, int G) {
;     ...
;         if (t + 2 * G < 3072) AT_LOAD(t + 2 * G, half);
	s_cmpk_gt_i32 s52, 0xbff
	s_cselect_b64 s[24:25], -1, 0
	s_and_b64 vcc, exec, s[24:25]
	s_cbranch_vccnz .LBB0_279
	s_ashr_i32 s21, s52, 4
	s_mul_hi_i32 s22, s21, 0x55555556
	s_lshr_b32 s23, s22, 31
	s_add_i32 s22, s22, s23
	s_mul_i32 s22, s22, 3
	s_sub_i32 s21, s21, s22
	s_mul_hi_i32 s22, s52, 0x2aaaaaab
	s_lshr_b32 s23, s22, 31
	s_ashr_i32 s22, s22, 3
	s_lshl_b32 s26, s21, 1
	s_and_b32 s20, s52, 15
	s_add_i32 s23, s22, s23
	s_lshl_b32 s30, -1, s26
	s_andn2_b32 s30, s20, s30
	s_lshr_b32 s31, s20, s26
	s_lshl_b32 s20, s23, 6
	s_ashr_i32 s22, s23, 4
	s_mulk_i32 s21, 0xc00
	s_and_b32 s20, s20, 0x3c0
	s_or_b32 s20, s21, s20
	s_ashr_i32 s23, s22, 31
	s_lshl_b64 s[22:23], s[22:23], 11
	s_ashr_i32 s21, s20, 31
	s_lshl_b32 s55, s31, 7
	s_or_b32 s22, s22, s30
	s_lshl_b64 s[30:31], s[20:21], 1
	v_mov_b32_e32 v6, v0
	v_mov_b32_e32 v7, v0
	v_add_u32_e32 v48, s55, v182
	s_add_u32 s38, s34, s30
	v_mov_b32_e32 v4, v0
	v_mov_b32_e32 v5, v0
	v_mov_b64_e32 v[10:11], v[6:7]
	v_mov_b64_e32 v[14:15], v[6:7]
	s_addc_u32 s39, s35, s31
	v_cmp_lt_i32_e32 vcc, -1, v48
	v_mov_b64_e32 v[8:9], v[4:5]
	v_mov_b64_e32 v[12:13], v[4:5]
	s_and_saveexec_b64 s[30:31], vcc
	s_cbranch_execz .LBB0_272
	v_mov_b32_e32 v49, v0
	v_lshlrev_b64 v[2:3], s26, v[48:49]
	v_lshl_add_u64 v[2:3], v[2:3], 0, s[22:23]
	v_mov_b64_e32 v[8:9], s[38:39]
	s_movk_i32 s80, 0x4800
	v_mad_u64_u32 v[8:9], vcc, v2, s80, v[8:9]
	v_mov_b32_e32 v2, v9
	v_mad_u64_u32 v[2:3], vcc, v3, s80, v[2:3]
	v_mov_b32_e32 v9, v2
	v_lshlrev_b32_e32 v2, 1, v108
	v_mov_b32_e32 v3, v0
	v_lshl_add_u64 v[2:3], v[8:9], 0, v[2:3]
	v_add_co_u32_e32 v12, vcc, 0x1000, v2
	s_nop 1
	v_addc_co_u32_e32 v13, vcc, 0, v3, vcc
	global_load_dwordx4 v[8:11], v[2:3], off offset:2048
	s_nop 0
	global_load_dwordx4 v[12:15], v[12:13], off

; #define LAS __attribute__((address_space(3)))
; __device__ __forceinline__ float bflo(unsigned u) { return __uint_as_float(u << 16); }
; __device__ __forceinline__ float bfhi(unsigned u) { return __uint_as_float(u & 0xffff0000u); }
; __device__ __forceinline__ unsigned pk2(float lo, float hi) { f32x2_t v = {lo, hi}; bf16x2_t b = __builtin_convertvector(v, bf16x2_t); return __builtin_bit_cast(unsigned, b); }
; #define LBAR() do { asm volatile("s_waitcnt lgkmcnt(0)" ::: "memory"); __builtin_amdgcn_s_barrier(); asm volatile("" ::: "memory"); } while (0)
; __device__ __forceinline__ void attn_phase(LAS unsigned char* lds, const bf16* PROJ, const bf16* Ygate, bf16* OG0, bf16* OG1, bf16* OG2, float* LSE, const float* qnw, const float* knw, int bx, int G) {
;     ...
;         const int sub = t & 15, gi = (t >> 4) % 3, bh = t / 48, h = bh & 15, bl = bh >> 4;
;         const int sh = 2 * gi, d = 1 << sh, r = sub & (d - 1), n = sub >> sh;
;         const float ad = exp2f(-8.f * (float)(gi * 16 + h + 1) / 48.f) * (float)d;
;         bf16* OG = gi == 0 ? OG0 : (gi == 1 ? OG1 : OG2);
;         {
;             const f32x4 kw0 = *(const f32x4*)(knw + gi * 64 + 8 * oct), kw1 = *(const f32x4*)(knw + gi * 64 + 8 * oct + 4);
; #pragma unroll
;             for (int jj = 0; jj < 4; ++jj) {
;                 const int key = (tid >> 3) + 64 * jj; const v4u kq = kr[half][jj];
;                 float kf[8] = {bflo(kq.x), bfhi(kq.x), bflo(kq.y), bfhi(kq.y), bflo(kq.z), bfhi(kq.z), bflo(kq.w), bfhi(kq.w)};
;                 float ss = 0.f;
; #pragma unroll
;                 for (int e = 0; e < 8; ++e) ss += kf[e] * kf[e];
;                 ss += __shfl_xor(ss, 1); ss += __shfl_xor(ss, 2); ss += __shfl_xor(ss, 4);
;                 const float rs = rsqrtf(ss * (1.f / 64.f) + EPS);
;                 v4u ko; ko.x = pk2(kf[0] * rs * kw0[0], kf[1] * rs * kw0[1]); ko.y = pk2(kf[2] * rs * kw0[2], kf[3] * rs * kw0[3]);
;                 ko.z = pk2(kf[4] * rs * kw1[0], kf[5] * rs * kw1[1]); ko.w = pk2(kf[6] * rs * kw1[2], kf[7] * rs * kw1[3]);
;                 *(LAS v4u*)(Ks + key * 72 + 8 * oct) = ko;
;                 *(LAS v4u*)(Vs + key * 80 + 8 * oct) = vr[half][jj];
;             }
;     ...
;         LBAR();
.LBB0_308:
	s_or_b64 exec, exec, s[0:1]
	s_waitcnt lgkmcnt(0)
	s_barrier
	s_add_i32 s0, s84, s51
	s_cmpk_gt_i32 s0, 0xbff
	s_cbranch_scc1 .LBB0_268
	s_ashr_i32 s1, s0, 4
	s_mul_hi_i32 s2, s1, 0x55555556
	s_lshr_b32 s3, s2, 31
	s_add_i32 s2, s2, s3
	s_mul_i32 s2, s2, 3
	s_sub_i32 s2, s1, s2
	s_and_b32 s22, s0, 15
	s_mul_hi_i32 s0, s0, 0x2aaaaaab
	s_lshl_b32 s3, s2, 1
	s_lshr_b32 s1, s0, 31
	s_ashr_i32 s23, s0, 3
	s_bfm_b32 s0, s3, 0
	s_and_b32 s26, s0, s22
	s_lshl_b32 s0, s2, 6
	s_add_i32 s23, s23, s1
	s_ashr_i32 s1, s0, 31
	s_lshl_b64 s[20:21], s[0:1], 2
	v_lshl_add_u64 v[2:3], v[110:111], 0, s[20:21]
	global_load_dwordx4 v[84:87], v[2:3], off offset:16
	global_load_dwordx4 v[88:91], v[2:3], off
	v_lshlrev_b32_e32 v102, 16, v32
	v_and_b32_e32 v103, 0xffff0000, v32
	v_lshlrev_b32_e32 v98, 16, v33
	v_and_b32_e32 v99, 0xffff0000, v33
	v_pk_mul_f32 v[104:105], v[102:103], v[102:103]
	v_pk_mul_f32 v[100:101], v[98:99], v[98:99]
	v_add_f32_e32 v1, v104, v105
	v_lshlrev_b32_e32 v94, 16, v34
	v_and_b32_e32 v95, 0xffff0000, v34
	v_add_f32_e32 v1, v100, v1
	v_pk_mul_f32 v[96:97], v[94:95], v[94:95]
	v_add_f32_e32 v1, v101, v1
	v_lshlrev_b32_e32 v2, 16, v35
	v_and_b32_e32 v3, 0xffff0000, v35
	v_add_f32_e32 v1, v96, v1
	v_pk_mul_f32 v[92:93], v[2:3], v[2:3]
	v_add_f32_e32 v1, v97, v1
	v_add_f32_e32 v1, v92, v1
	v_add_f32_e32 v1, v93, v1
	s_nop 1
	v_mov_b32_dpp v92, v1 quad_perm:[1,0,3,2] row_mask:0xf bank_mask:0xf
	v_lshlrev_b32_e32 v158, 16, v60
	v_and_b32_e32 v159, 0xffff0000, v60
	v_lshlrev_b32_e32 v154, 16, v61
	v_and_b32_e32 v155, 0xffff0000, v61
	s_waitcnt lgkmcnt(0)
	v_add_f32_e32 v1, v1, v92
	s_nop 1
	v_mov_b32_dpp v92, v1 quad_perm:[2,3,0,1] row_mask:0xf bank_mask:0xf
	v_pk_mul_f32 v[162:163], v[158:159], v[158:159]
	v_pk_mul_f32 v[156:157], v[154:155], v[154:155]
	v_mov_b32_e32 v164, v162
	v_lshlrev_b32_e32 v150, 16, v62
	s_waitcnt lgkmcnt(0)
	v_add_f32_e32 v1, v1, v92
	s_nop 1
	v_mov_b32_dpp v92, v1 row_half_mirror row_mask:0xf bank_mask:0xf
	v_and_b32_e32 v151, 0xffff0000, v62
	v_mov_b32_e32 v162, v156
	v_pk_mul_f32 v[152:153], v[150:151], v[150:151]
	v_lshlrev_b32_e32 v106, 16, v63
	s_waitcnt lgkmcnt(0)
	v_add_f32_e32 v1, v1, v92
	v_fmamk_f32 v1, v1, 0x3c800000, v139
	v_cmp_gt_f32_e32 vcc, s33, v1
	v_mul_f32_e32 v92, 0x4b800000, v1
	v_and_b32_e32 v107, 0xffff0000, v63
	v_cndmask_b32_e32 v1, v1, v92, vcc
	v_rsq_f32_e32 v1, v1
	v_pk_mul_f32 v[136:137], v[106:107], v[106:107]
	s_mov_b32 s0, 0x358637bd
	s_mov_b32 s38, 0x3c800000
	v_mul_f32_e32 v92, 0x45800000, v1
	v_cndmask_b32_e32 v96, v1, v92, vcc
	v_pk_mul_f32 v[92:93], v[96:97], v[102:103] op_sel_hi:[0,1]
	v_pk_mul_f32 v[98:99], v[96:97], v[98:99] op_sel_hi:[0,1]
	v_pk_mul_f32 v[94:95], v[96:97], v[94:95] op_sel_hi:[0,1]
	v_pk_mul_f32 v[2:3], v[96:97], v[2:3] op_sel_hi:[0,1]
	v_lshlrev_b32_e32 v102, 16, v28
	v_and_b32_e32 v103, 0xffff0000, v28
	v_pk_mul_f32 v[104:105], v[102:103], v[102:103]
	v_and_b32_e32 v179, 0xffff0000, v76
	v_mov_b32_e32 v165, v104
	v_mov_b32_e32 v104, v163
	v_pk_add_f32 v[104:105], v[164:165], v[104:105]
	v_lshlrev_b32_e32 v178, 16, v76
	v_mul_f32_e32 v242, v179, v179
	v_lshlrev_b32_e32 v176, 16, v77
	v_and_b32_e32 v177, 0xffff0000, v77
	v_pk_fma_f32 v[242:243], v[178:179], v[178:179], v[242:243] op_sel_hi:[1,1,0]
	v_mul_f32_e32 v244, v177, v177
	v_pk_fma_f32 v[242:243], v[176:177], v[176:177], v[242:243]
	v_lshlrev_b32_e32 v174, 16, v78
	v_and_b32_e32 v175, 0xffff0000, v78
	v_pk_add_f32 v[242:243], v[244:245], v[242:243] op_sel_hi:[0,1]
	v_pk_fma_f32 v[242:243], v[174:175], v[174:175], v[242:243]
	v_mul_f32_e32 v244, v175, v175
	v_lshlrev_b32_e32 v172, 16, v79
	v_and_b32_e32 v173, 0xffff0000, v79
	v_pk_add_f32 v[242:243], v[244:245], v[242:243] op_sel_hi:[0,1]
	v_lshlrev_b32_e32 v232, 16, v68
	v_and_b32_e32 v233, 0xffff0000, v68
	v_lshlrev_b32_e32 v170, 16, v80
	v_and_b32_e32 v171, 0xffff0000, v80
	s_waitcnt vmcnt(1)
	v_pk_mul_f32 v[94:95], v[84:85], v[94:95]
	s_waitcnt vmcnt(0)
	v_pk_mul_f32 v[92:93], v[88:89], v[92:93]
	v_pk_mul_f32 v[98:99], v[90:91], v[98:99]
	v_cvt_pk_bf16_f32 v92, v92, v93
	v_cvt_pk_bf16_f32 v93, v98, v99
	v_pk_mul_f32 v[2:3], v[86:87], v[2:3]
	v_lshlrev_b32_e32 v98, 16, v29
	v_and_b32_e32 v99, 0xffff0000, v29
	v_cvt_pk_bf16_f32 v94, v94, v95
	v_cvt_pk_bf16_f32 v95, v2, v3
	v_pk_mul_f32 v[100:101], v[98:99], v[98:99]
	ds_write_b128 v229, v[92:95]
	ds_write_b128 v231, v[36:39] offset:36864
	v_lshlrev_b32_e32 v94, 16, v30
	v_and_b32_e32 v95, 0xffff0000, v30
	v_mov_b32_e32 v163, v100
	v_pk_mul_f32 v[96:97], v[94:95], v[94:95]
	v_pk_add_f32 v[104:105], v[162:163], v[104:105]
	v_mov_b32_e32 v100, v157
	v_lshlrev_b32_e32 v2, 16, v31
	v_and_b32_e32 v3, 0xffff0000, v31
	v_pk_add_f32 v[100:101], v[100:101], v[104:105]
	v_mov_b32_e32 v104, v152
	v_mov_b32_e32 v105, v96
	v_pk_mul_f32 v[92:93], v[2:3], v[2:3]
	v_pk_add_f32 v[100:101], v[104:105], v[100:101]
	v_mov_b32_e32 v96, v153
	v_pk_add_f32 v[96:97], v[96:97], v[100:101]
	v_mov_b32_e32 v100, v136
	v_mov_b32_e32 v101, v92
	v_pk_add_f32 v[96:97], v[100:101], v[96:97]
	v_mov_b32_e32 v92, v137
	v_pk_add_f32 v[92:93], v[92:93], v[96:97]
	s_nop 1
	v_mov_b32_dpp v97, v93 quad_perm:[1,0,3,2] row_mask:0xf bank_mask:0xf
	s_nop 1
	v_mov_b32_dpp v96, v92 quad_perm:[1,0,3,2] row_mask:0xf bank_mask:0xf
	v_mov_b64_e32 v[136:137], s[0:1]
	v_pk_fma_f32 v[242:243], v[172:173], v[172:173], v[242:243]
	v_mul_f32_e32 v244, v173, v173
	v_pk_mul_f32 v[180:181], v[232:233], v[232:233]
	s_waitcnt lgkmcnt(0)
	v_pk_add_f32 v[92:93], v[92:93], v[96:97]
	s_nop 1
	v_mov_b32_dpp v97, v93 quad_perm:[2,3,0,1] row_mask:0xf bank_mask:0xf
	s_nop 1
	v_mov_b32_dpp v96, v92 quad_perm:[2,3,0,1] row_mask:0xf bank_mask:0xf
	v_pk_mul_f32 v[240:241], v[170:171], v[170:171]
	v_pk_add_f32 v[242:243], v[244:245], v[242:243] op_sel_hi:[0,1]
	v_lshlrev_b32_e32 v168, 16, v81
	v_and_b32_e32 v169, 0xffff0000, v81
	s_waitcnt lgkmcnt(0)
; #define LAS __attribute__((address_space(3)))
; __device__ __forceinline__ void attn_phase(LAS unsigned char* lds, const bf16* PROJ, const bf16* Ygate, bf16* OG0, bf16* OG1, bf16* OG2, float* LSE, const float* qnw, const float* knw, int bx, int G) {
;     ...
;             const f32x4 kw0 = *(const f32x4*)(knw + gi * 64 + 8 * oct), kw1 = *(const f32x4*)(knw + gi * 64 + 8 * oct + 4);
; #pragma unroll
;             for (int jj = 0; jj < 4; ++jj) {
;                 const int key = (tid >> 3) + 64 * jj; const v4u kq = kr[half][jj];
;                 float kf[8] = {bflo(kq.x), bfhi(kq.x), bflo(kq.y), bfhi(kq.y), bflo(kq.z), bfhi(kq.z), bflo(kq.w), bfhi(kq.w)};
;                 float ss = 0.f;
; #pragma unroll
;                 for (int e = 0; e < 8; ++e) ss += kf[e] * kf[e];
;                 ss += __shfl_xor(ss, 1); ss += __shfl_xor(ss, 2); ss += __shfl_xor(ss, 4);
;                 const float rs = rsqrtf(ss * (1.f / 64.f) + EPS);
;                 v4u ko; ko.x = pk2(kf[0] * rs * kw0[0], kf[1] * rs * kw0[1]); ko.y = pk2(kf[2] * rs * kw0[2], kf[3] * rs * kw0[3]);
;                 ko.z = pk2(kf[4] * rs * kw1[0], kf[5] * rs * kw1[1]); ko.w = pk2(kf[6] * rs * kw1[2], kf[7] * rs * kw1[3]);
;                 *(LAS v4u*)(Ks + key * 72 + 8 * oct) = ko;
;                 *(LAS v4u*)(Vs + key * 80 + 8 * oct) = vr[half][jj];
;             }
;         }
;         const int qi = 16 * w + l16;
;         const size_t qrow = (size_t)bl * SEQL + (size_t)(128 * n + qi) * d + r;
;         bf16x8 qreg[2];
;         {
;             float qf[2][8]; float ss = 0.f;
; #pragma unroll
;             for (int ks = 0; ks < 2; ++ks) {
;                 const v4u qq = qr[half][ks];
;                 qf[ks][0] = bflo(qq.x); qf[ks][1] = bfhi(qq.x); qf[ks][2] = bflo(qq.y); qf[ks][3] = bfhi(qq.y); qf[ks][4] = bflo(qq.z); qf[ks][5] = bfhi(qq.z); qf[ks][6] = bflo(qq.w); qf[ks][7] = bfhi(qq.w);
; #pragma unroll
;                 for (int e = 0; e < 8; ++e) ss += qf[ks][e] * qf[ks][e];
;             }
;             ss += __shfl_xor(ss, 16); ss += __shfl_xor(ss, 32);
;             const float rs = rsqrtf(ss * (1.f / 64.f) + EPS) * 0.125f;
; #pragma unroll
;             for (int ks = 0; ks < 2; ++ks) {
;                 const f32x4 w0 = *(const f32x4*)(qnw + gi * 64 + 32 * ks + 8 * g4), w1 = *(const f32x4*)(qnw + gi * 64 + 32 * ks + 8 * g4 + 4);
	v_pk_add_f32 v[92:93], v[92:93], v[96:97]
	s_nop 1
	v_mov_b32_dpp v97, v93 row_half_mirror row_mask:0xf bank_mask:0xf
	s_nop 1
	v_mov_b32_dpp v96, v92 row_half_mirror row_mask:0xf bank_mask:0xf
	v_mov_b32_e32 v244, v240
	v_mov_b32_e32 v245, v180
	v_mov_b32_e32 v243, v181
	v_pk_mul_f32 v[238:239], v[168:169], v[168:169]
	s_waitcnt lgkmcnt(0)
	v_pk_add_f32 v[92:93], v[92:93], v[96:97]
	v_pk_add_f32 v[180:181], v[244:245], v[242:243]
	v_pk_fma_f32 v[96:97], v[92:93], s[38:39], v[136:137] op_sel_hi:[1,0,0]
	v_lshlrev_b32_e32 v166, 16, v82
	v_mul_f32_e32 v1, 0x4b800000, v97
	v_cmp_gt_f32_e64 s[0:1], s33, v97
	v_cmp_gt_f32_e32 vcc, s33, v96
	v_and_b32_e32 v167, 0xffff0000, v82
	v_cndmask_b32_e64 v1, v97, v1, s[0:1]
	v_rsq_f32_e32 v1, v1
	v_pk_mul_f32 v[236:237], v[166:167], v[166:167]
	v_lshlrev_b32_e32 v164, 16, v83
	v_and_b32_e32 v165, 0xffff0000, v83
	v_mul_f32_e32 v92, 0x45800000, v1
	v_cndmask_b32_e64 v100, v1, v92, s[0:1]
	v_mul_f32_e32 v1, 0x4b800000, v96
	v_cndmask_b32_e32 v1, v96, v1, vcc
	v_rsq_f32_e32 v1, v1
	v_pk_mul_f32 v[94:95], v[100:101], v[94:95] op_sel_hi:[0,1]
	v_pk_mul_f32 v[2:3], v[100:101], v[2:3] op_sel_hi:[0,1]
	v_pk_mul_f32 v[92:93], v[100:101], v[102:103] op_sel_hi:[0,1]
	v_pk_mul_f32 v[98:99], v[100:101], v[98:99] op_sel_hi:[0,1]
	v_pk_mul_f32 v[94:95], v[84:85], v[94:95]
	v_pk_mul_f32 v[2:3], v[86:87], v[2:3]
	v_pk_mul_f32 v[92:93], v[88:89], v[92:93]
	v_pk_mul_f32 v[98:99], v[90:91], v[98:99]
	v_cvt_pk_bf16_f32 v94, v94, v95
	v_cvt_pk_bf16_f32 v95, v2, v3
	v_mul_f32_e32 v2, 0x45800000, v1
	v_cvt_pk_bf16_f32 v92, v92, v93
	v_cvt_pk_bf16_f32 v93, v98, v99
	v_cndmask_b32_e32 v2, v1, v2, vcc
	ds_write_b128 v229, v[92:95] offset:9216
	ds_write_b128 v231, v[56:59] offset:47104
	v_pk_mul_f32 v[92:93], v[2:3], v[158:159] op_sel_hi:[0,1]
	v_lshlrev_b32_e32 v158, 16, v69
	v_and_b32_e32 v159, 0xffff0000, v69
	v_pk_mul_f32 v[162:163], v[158:159], v[158:159]
	v_pk_mul_f32 v[94:95], v[2:3], v[154:155] op_sel_hi:[0,1]
	v_lshlrev_b32_e32 v154, 16, v70
	v_and_b32_e32 v155, 0xffff0000, v70
	v_pk_mov_b32 v[240:241], v[240:241], v[162:163] op_sel:[1,0]
	v_pk_mul_f32 v[92:93], v[88:89], v[92:93]
	v_pk_mul_f32 v[94:95], v[90:91], v[94:95]
	v_pk_mul_f32 v[156:157], v[154:155], v[154:155]
	v_pk_add_f32 v[180:181], v[240:241], v[180:181]
	v_mov_b32_e32 v162, v238
	v_cvt_pk_bf16_f32 v92, v92, v93
	v_cvt_pk_bf16_f32 v93, v94, v95
	v_pk_mul_f32 v[94:95], v[2:3], v[150:151] op_sel_hi:[0,1]
	v_lshlrev_b32_e32 v150, 16, v71
	v_and_b32_e32 v151, 0xffff0000, v71
	v_pk_add_f32 v[162:163], v[162:163], v[180:181]
	v_pk_mov_b32 v[180:181], v[238:239], v[156:157] op_sel:[1,0]
	v_pk_mul_f32 v[152:153], v[150:151], v[150:151]
	v_pk_add_f32 v[162:163], v[180:181], v[162:163]
	v_mov_b32_e32 v156, v236
	v_pk_mul_f32 v[234:235], v[164:165], v[164:165]
	v_pk_add_f32 v[156:157], v[156:157], v[162:163]
	v_pk_mov_b32 v[162:163], v[236:237], v[152:153] op_sel:[1,0]
	v_mov_b32_e32 v152, v234
	v_pk_add_f32 v[156:157], v[162:163], v[156:157]
	v_pk_mul_f32 v[2:3], v[2:3], v[106:107] op_sel_hi:[0,1]
	v_pk_add_f32 v[152:153], v[152:153], v[156:157]
	s_nop 1
	v_mov_b32_dpp v157, v153 quad_perm:[1,0,3,2] row_mask:0xf bank_mask:0xf
	v_mov_b32_e32 v156, v235
	v_pk_mul_f32 v[94:95], v[84:85], v[94:95]
	v_pk_mul_f32 v[2:3], v[86:87], v[2:3]
	s_ashr_i32 s0, s23, 4
	s_waitcnt lgkmcnt(0)
	v_pk_add_f32 v[152:153], v[156:157], v[152:153]
	s_nop 1
	v_mov_b32_dpp v157, v153 quad_perm:[2,3,0,1] row_mask:0xf bank_mask:0xf
	ds_bpermute_b32 v156, v189, v152
	s_lshr_b32 s54, s22, s3
	v_cvt_pk_bf16_f32 v94, v94, v95
	v_cvt_pk_bf16_f32 v95, v2, v3
	s_ashr_i32 s1, s0, 31
	s_waitcnt lgkmcnt(0)
	v_pk_add_f32 v[152:153], v[152:153], v[156:157]
	s_nop 1
	v_mov_b32_dpp v157, v153 row_half_mirror row_mask:0xf bank_mask:0xf
	ds_bpermute_b32 v156, v196, v152
	v_lshl_add_u32 v2, s54, 7, v147
	s_and_b32 s53, s23, 15
	s_lshl_b64 s[22:23], s[0:1], 11
	v_ashrrev_i32_e32 v3, 31, v2
	s_waitcnt lgkmcnt(0)
	v_pk_add_f32 v[152:153], v[152:153], v[156:157]
	s_or_b32 s22, s22, s26
	v_pk_fma_f32 v[180:181], v[152:153], s[38:39], v[136:137] op_sel_hi:[1,0,0]
	v_lshlrev_b64 v[2:3], s3, v[2:3]
	v_mul_f32_e32 v1, 0x4b800000, v181
	v_cmp_gt_f32_e32 vcc, s33, v181
	ds_write_b128 v229, v[92:95] offset:18432
	ds_write_b128 v231, v[64:67] offset:57344
	v_cndmask_b32_e32 v1, v181, v1, vcc
	v_rsq_f32_e32 v1, v1
	v_lshl_add_u64 v[96:97], v[114:115], 0, s[20:21]
	s_lshl_b32 s26, s53, 7
	global_load_dwordx4 v[100:103], v[96:97], off offset:16
	global_load_dwordx4 v[104:107], v[96:97], off
	global_load_dwordx4 v[92:95], v[96:97], off offset:144
	s_nop 0
	global_load_dwordx4 v[96:99], v[96:97], off offset:128
	v_mul_f32_e32 v135, 0x45800000, v1
	v_cndmask_b32_e32 v136, v1, v135, vcc
	v_pk_mul_f32 v[152:153], v[136:137], v[232:233] op_sel_hi:[0,1]
	v_pk_mul_f32 v[88:89], v[88:89], v[152:153]
	v_pk_mul_f32 v[152:153], v[136:137], v[158:159] op_sel_hi:[0,1]
	v_pk_mul_f32 v[90:91], v[90:91], v[152:153]
	v_cvt_pk_bf16_f32 v88, v88, v89
	v_cvt_pk_bf16_f32 v89, v90, v91
	v_pk_mul_f32 v[90:91], v[136:137], v[154:155] op_sel_hi:[0,1]
	v_pk_mul_f32 v[84:85], v[84:85], v[90:91]
	v_mov_b32_e32 v135, v0
	v_cvt_pk_bf16_f32 v90, v84, v85
	v_pk_mul_f32 v[84:85], v[136:137], v[150:151] op_sel_hi:[0,1]
	v_lshl_add_u64 v[136:137], s[22:23], 0, v[2:3]
	v_lshlrev_b64 v[162:163], 11, v[136:137]
	v_pk_mul_f32 v[84:85], v[86:87], v[84:85]
	v_lshl_add_u64 v[2:3], s[28:29], 0, v[162:163]
	v_cvt_pk_bf16_f32 v91, v84, v85
	v_lshl_add_u64 v[2:3], v[2:3], 0, s[26:27]
	ds_write_b128 v229, v[88:91] offset:27648
	ds_write_b128 v230, v[72:75] offset:57344
	v_lshl_add_u64 v[2:3], v[2:3], 0, v[134:135]
	global_load_dwordx4 v[88:91], v[2:3], off
	global_load_dwordx4 v[84:87], v[2:3], off offset:64
	s_waitcnt lgkmcnt(0)
	s_barrier
; __device__ __forceinline__ void attn_phase(LAS unsigned char* lds, const bf16* PROJ, const bf16* Ygate, bf16* OG0, bf16* OG1, bf16* OG2, float* LSE, const float* qnw, const float* knw, int bx, int G) {
;     ...
;         if (t + 2 * G < 3072) AT_LOAD(t + 2 * G, half);
	s_mul_i32 s20, s84, 3
	s_add_i32 s20, s20, s51
	v_cmp_gt_f32_e64 s[0:1], s33, v180
	s_cmpk_gt_i32 s20, 0xbff
	s_cbranch_scc1 .LBB0_319
	s_ashr_i32 s22, s20, 4
	s_mul_hi_i32 s23, s22, 0x55555556
	s_lshr_b32 s26, s23, 31
	s_add_i32 s23, s23, s26
	s_and_b32 s21, s20, 15
	s_mul_i32 s23, s23, 3
	s_mul_hi_i32 s20, s20, 0x2aaaaaab
	s_sub_i32 s23, s22, s23
	s_lshr_b32 s22, s20, 31
	s_ashr_i32 s20, s20, 3
	s_add_i32 s20, s20, s22
	s_ashr_i32 s22, s20, 4
	s_lshl_b32 s26, s23, 1
	s_lshl_b32 s20, s20, 6
	s_lshl_b32 s30, -1, s26
	s_mulk_i32 s23, 0xc00
	s_and_b32 s20, s20, 0x3c0
	s_andn2_b32 s30, s21, s30
	s_lshr_b32 s21, s21, s26
	s_or_b32 s20, s23, s20
	s_ashr_i32 s23, s22, 31
	s_lshl_b32 s51, s21, 7
	s_lshl_b64 s[22:23], s[22:23], 11
	s_ashr_i32 s21, s20, 31
	s_or_b32 s22, s22, s30
	s_lshl_b64 s[30:31], s[20:21], 1
	v_mov_b32_e32 v30, v0
	v_mov_b32_e32 v31, v0
	v_add_u32_e32 v76, s51, v182
	s_add_u32 s38, s34, s30
	v_mov_b32_e32 v28, v0
	v_mov_b32_e32 v29, v0
	v_mov_b64_e32 v[34:35], v[30:31]
	v_mov_b64_e32 v[38:39], v[30:31]
	s_addc_u32 s39, s35, s31
	v_cmp_lt_i32_e32 vcc, -1, v76
	v_lshlrev_b32_e32 v78, 1, v108
	v_mov_b64_e32 v[32:33], v[28:29]
	v_mov_b64_e32 v[36:37], v[28:29]
	s_and_saveexec_b64 s[30:31], vcc
	s_cbranch_execz .LBB0_312
	v_mov_b32_e32 v77, v0
	v_lshlrev_b64 v[2:3], s26, v[76:77]
	v_lshl_add_u64 v[2:3], v[2:3], 0, s[22:23]
	v_mov_b64_e32 v[32:33], s[38:39]
	s_movk_i32 s55, 0x4800
	v_mad_u64_u32 v[32:33], vcc, v2, s55, v[32:33]
	v_mov_b32_e32 v2, v33
	v_mad_u64_u32 v[2:3], vcc, v3, s55, v[2:3]
	v_mov_b32_e32 v33, v2
	v_mov_b32_e32 v79, v0
	v_lshl_add_u64 v[2:3], v[32:33], 0, v[78:79]
	v_add_co_u32_e32 v36, vcc, 0x1000, v2
	s_nop 1
	v_addc_co_u32_e32 v37, vcc, 0, v3, vcc
	global_load_dwordx4 v[32:35], v[2:3], off offset:2048
	s_nop 0
	global_load_dwordx4 v[36:39], v[36:37], off
